# combination of individually bit-exact edits on v58: MoBA gate loads merged, a1 task prologue one round trip, compacted conflict-free LUT for the class-major jobs, raised priority over the tile compute
# speedup vs baseline: 1.0000x; 1.0000x over previous
; #define LAS __attribute__((address_space(3)))
; DI void attn_dma(const AttnCtx& c, int kt) {
;     const char* kb = (const char*)(c.kg + (size_t)(kt * 32 * c.krs) * RM_LD);
;     const char* vb = (const char*)(c.vg + kt * 32);
; #pragma unroll
;     for (int j = 0; j < 4; ++j) __builtin_amdgcn_global_load_lds((const unsigned*)(kb + c.koff[j]), (LAS unsigned*)(c.wl + j * 1024), 16, 0, 0);
; #pragma unroll
;     for (int j = 0; j < 4; ++j) __builtin_amdgcn_global_load_lds((const unsigned*)(vb + c.voff[j]), (LAS unsigned*)(c.wl + 4096 + j * 1024), 16, 0, 0);
; }
; template <int MODE>
; DI void attn_range(const AttnCtx& c, const bf16x8 (&qf)[4], int lo, int hi, int t0, int d00, AttnSt& st, const unsigned* maskrow, int h8, int win, int dmask, bool lane_sel) {
;     ...
;     for (int kt = lo; kt <= hi; ++kt) {
;         asm volatile("s_waitcnt vmcnt(0)" ::: "memory");
;         bf16x8 kf[4], vf[2][2];
; #pragma unroll
;         for (int ks = 0; ks < 4; ++ks) kf[ks] = *(const LAS bf16x8*)(c.wl + c.kfo[ks]);
; #pragma unroll
;         for (int mt = 0; mt < 2; ++mt)
; #pragma unroll
;             for (int s = 0; s < 2; ++s) vf[mt][s] = *(const LAS bf16x8*)(c.wl + 4096 + c.vfo[mt][s]);
;         const unsigned W = Wn >> h8;
;         const int dlo = t0 - kt * 32 - 31;
;         float ub = 0.f; bool uni = false;
;         if (dlo >= 182) { const unsigned ua = __builtin_amdgcn_readfirstlane(__float_as_uint(c.lut[dlo])), ue = __builtin_amdgcn_readfirstlane(__float_as_uint(c.lut[dlo + 62])); uni = (ua == ue); ub = __uint_as_float(ua); }
;         asm volatile("s_waitcnt lgkmcnt(0)" ::: "memory");
;         if (kt < hi) { attn_dma(c, kt + 1); if (MODE == 0) Wn = maskrow[kt + 1]; }
.LBB0_283:
	s_waitcnt vmcnt(0)
	s_waitcnt lgkmcnt(0)
	ds_read_b128 v[106:109], v214
	ds_read_b128 v[110:113], v215
	ds_read_b128 v[102:105], v216
	ds_read_b128 v[98:101], v217
	ds_read_b128 v[94:97], v218 offset:4096
	ds_read_b128 v[86:89], v218 offset:6144
	ds_read_b128 v[90:93], v219 offset:4096
	ds_read_b128 v[82:85], v219 offset:6144
	s_waitcnt lgkmcnt(0)
	s_cmp_ge_i32 s69, s57
	s_cselect_b64 s[8:9], -1, 0
	s_and_b64 vcc, exec, s[8:9]
	s_cbranch_vccnz .LBB0_285
	s_add_i32 s7, s6, 32
	s_mul_hi_i32 s47, s7, 0x1600
	s_mulk_i32 s7, 0x1600
	s_add_u32 s46, s1, s7
	s_addc_u32 s47, s66, s47
	s_add_u32 s46, s46, s20
	s_addc_u32 s47, s47, s21
	s_mov_b32 m0, s49
	s_nop 0
	global_load_lds_dwordx4 v116, s[46:47] sc0
	s_mov_b32 m0, s2
	s_nop 0
	global_load_lds_dwordx4 v118, s[46:47] sc0
	s_mov_b32 m0, s70
	s_nop 0
	global_load_lds_dwordx4 v122, s[46:47] sc0
	s_mov_b32 m0, s53
	s_nop 0
	global_load_lds_dwordx4 v126, s[46:47] sc0
	s_ashr_i32 s7, s6, 31
	s_lshl_b64 s[46:47], s[6:7], 1
	s_add_u32 s46, s67, s46
	s_addc_u32 s47, s68, s47
	s_add_u32 s74, s46, 64
	s_addc_u32 s75, s47, 0
	s_mov_b32 m0, s71
	s_nop 0
	global_load_lds_dwordx4 v114, s[74:75] sc0
	s_mov_b32 m0, s54
	s_nop 0
	global_load_lds_dwordx4 v120, s[74:75] sc0
	s_mov_b32 m0, s72
	s_nop 0
	global_load_lds_dwordx4 v124, s[74:75] sc0
	s_mov_b32 m0, s55
	s_nop 0
	global_load_lds_dwordx4 v128, s[74:75] sc0

; #define LAS __attribute__((address_space(3)))
; DI void attn_dma(const AttnCtx& c, int kt) {
;     const char* kb = (const char*)(c.kg + (size_t)(kt * 32 * c.krs) * RM_LD);
;     const char* vb = (const char*)(c.vg + kt * 32);
; #pragma unroll
;     for (int j = 0; j < 4; ++j) __builtin_amdgcn_global_load_lds((const unsigned*)(kb + c.koff[j]), (LAS unsigned*)(c.wl + j * 1024), 16, 0, 0);
; #pragma unroll
;     for (int j = 0; j < 4; ++j) __builtin_amdgcn_global_load_lds((const unsigned*)(vb + c.voff[j]), (LAS unsigned*)(c.wl + 4096 + j * 1024), 16, 0, 0);
; }
; template <int MODE>
; DI void attn_range(const AttnCtx& c, const bf16x8 (&qf)[4], int lo, int hi, int t0, int d00, AttnSt& st, const unsigned* maskrow, int h8, int win, int dmask, bool lane_sel) {
;     ...
;     for (int kt = lo; kt <= hi; ++kt) {
;         asm volatile("s_waitcnt vmcnt(0)" ::: "memory");
;         bf16x8 kf[4], vf[2][2];
; #pragma unroll
;         for (int ks = 0; ks < 4; ++ks) kf[ks] = *(const LAS bf16x8*)(c.wl + c.kfo[ks]);
; #pragma unroll
;         for (int mt = 0; mt < 2; ++mt)
; #pragma unroll
;             for (int s = 0; s < 2; ++s) vf[mt][s] = *(const LAS bf16x8*)(c.wl + 4096 + c.vfo[mt][s]);
;         const unsigned W = Wn >> h8;
;         const int dlo = t0 - kt * 32 - 31;
;         float ub = 0.f; bool uni = false;
;         if (dlo >= 182) { const unsigned ua = __builtin_amdgcn_readfirstlane(__float_as_uint(c.lut[dlo])), ue = __builtin_amdgcn_readfirstlane(__float_as_uint(c.lut[dlo + 62])); uni = (ua == ue); ub = __uint_as_float(ua); }
;         asm volatile("s_waitcnt lgkmcnt(0)" ::: "memory");
;         if (kt < hi) { attn_dma(c, kt + 1); if (MODE == 0) Wn = maskrow[kt + 1]; }
.LBB0_302:
	s_waitcnt vmcnt(0)
	s_waitcnt lgkmcnt(0)
	ds_read_b128 v[106:109], v214
	ds_read_b128 v[110:113], v215
	ds_read_b128 v[102:105], v216
	ds_read_b128 v[98:101], v217
	ds_read_b128 v[94:97], v218 offset:4096
	ds_read_b128 v[86:89], v218 offset:6144
	ds_read_b128 v[90:93], v219 offset:4096
	ds_read_b128 v[82:85], v219 offset:6144
	s_waitcnt lgkmcnt(0)
	s_cmp_ge_i32 s66, s57
	s_cselect_b64 s[8:9], -1, 0
	s_and_b64 vcc, exec, s[8:9]
	s_cbranch_vccnz .LBB0_304
	s_add_i32 s7, s6, 32
	s_mul_hi_i32 s47, s7, 0x1600
	s_mulk_i32 s7, 0x1600
	s_add_u32 s46, s63, s7
	s_addc_u32 s47, s64, s47
	s_add_u32 s46, s46, s20
	s_addc_u32 s47, s47, s21
	s_mov_b32 m0, s49
	s_nop 0
	global_load_lds_dwordx4 v116, s[46:47] sc0
	s_mov_b32 m0, s2
	s_nop 0
	global_load_lds_dwordx4 v118, s[46:47] sc0
	s_mov_b32 m0, s67
	s_nop 0
	global_load_lds_dwordx4 v122, s[46:47] sc0
	s_mov_b32 m0, s53
	s_nop 0
	global_load_lds_dwordx4 v126, s[46:47] sc0
	s_ashr_i32 s7, s6, 31
	s_lshl_b64 s[46:47], s[6:7], 1
	s_add_u32 s46, s61, s46
	s_addc_u32 s47, s62, s47
	s_add_u32 s70, s46, 64
	s_addc_u32 s71, s47, 0
	s_mov_b32 m0, s68
	s_nop 0
	global_load_lds_dwordx4 v114, s[70:71] sc0
	s_mov_b32 m0, s54
	s_nop 0
	global_load_lds_dwordx4 v120, s[70:71] sc0
	s_mov_b32 m0, s69
	s_nop 0
	global_load_lds_dwordx4 v124, s[70:71] sc0
	s_mov_b32 m0, s55
	s_nop 0
	global_load_lds_dwordx4 v128, s[70:71] sc0

; #define LAS __attribute__((address_space(3)))
; DI void attn_dma(const AttnCtx& c, int kt) {
;     const char* kb = (const char*)(c.kg + (size_t)(kt * 32 * c.krs) * RM_LD);
;     const char* vb = (const char*)(c.vg + kt * 32);
; #pragma unroll
;     for (int j = 0; j < 4; ++j) __builtin_amdgcn_global_load_lds((const unsigned*)(kb + c.koff[j]), (LAS unsigned*)(c.wl + j * 1024), 16, 0, 0);
; #pragma unroll
;     for (int j = 0; j < 4; ++j) __builtin_amdgcn_global_load_lds((const unsigned*)(vb + c.voff[j]), (LAS unsigned*)(c.wl + 4096 + j * 1024), 16, 0, 0);
; }
; template <int MODE>
; DI void attn_range(const AttnCtx& c, const bf16x8 (&qf)[4], int lo, int hi, int t0, int d00, AttnSt& st, const unsigned* maskrow, int h8, int win, int dmask, bool lane_sel) {
;     if (lo > hi) return;
;     attn_dma(c, lo);
.Lmk_skip:
	s_mul_i32 s62, s2, 0x1600
	s_mul_hi_i32 s61, s2, 0x1600
	s_add_u32 s62, s0, s62
	s_addc_u32 s63, s1, s61
	s_add_u32 s62, s62, s64
	s_addc_u32 s63, s63, s65
	s_mov_b32 m0, s49
	s_nop 0
	global_load_lds_dwordx4 v116, s[62:63] sc0
	s_mov_b32 m0, s7
	s_nop 0
	global_load_lds_dwordx4 v118, s[62:63] sc0
	s_mov_b32 m0, s9
	s_nop 0
	global_load_lds_dwordx4 v122, s[62:63] sc0
	s_mov_b32 m0, s53
	s_nop 0
	global_load_lds_dwordx4 v126, s[62:63] sc0
	s_lshl_b64 s[62:63], s[2:3], 1
	s_add_u32 s62, s4, s62
	s_addc_u32 s63, s5, s63
	s_mov_b32 m0, s46
	s_nop 0
	global_load_lds_dwordx4 v114, s[62:63] sc0
	s_mov_b32 m0, s54
	s_nop 0
	global_load_lds_dwordx4 v120, s[62:63] sc0
	s_mov_b32 m0, s47
	s_nop 0
	global_load_lds_dwordx4 v124, s[62:63] sc0
	s_mov_b32 m0, s55
	s_nop 0
	global_load_lds_dwordx4 v128, s[62:63] sc0

; #define LAS __attribute__((address_space(3)))
; DI void attn_dma(const AttnCtx& c, int kt) {
;     const char* kb = (const char*)(c.kg + (size_t)(kt * 32 * c.krs) * RM_LD);
;     const char* vb = (const char*)(c.vg + kt * 32);
; #pragma unroll
;     for (int j = 0; j < 4; ++j) __builtin_amdgcn_global_load_lds((const unsigned*)(kb + c.koff[j]), (LAS unsigned*)(c.wl + j * 1024), 16, 0, 0);
; #pragma unroll
;     for (int j = 0; j < 4; ++j) __builtin_amdgcn_global_load_lds((const unsigned*)(vb + c.voff[j]), (LAS unsigned*)(c.wl + 4096 + j * 1024), 16, 0, 0);
; }
; template <int MODE>
; DI void attn_range(const AttnCtx& c, const bf16x8 (&qf)[4], int lo, int hi, int t0, int d00, AttnSt& st, const unsigned* maskrow, int h8, int win, int dmask, bool lane_sel) {
;     ...
;     for (int kt = lo; kt <= hi; ++kt) {
;         asm volatile("s_waitcnt vmcnt(0)" ::: "memory");
;         bf16x8 kf[4], vf[2][2];
; #pragma unroll
;         for (int ks = 0; ks < 4; ++ks) kf[ks] = *(const LAS bf16x8*)(c.wl + c.kfo[ks]);
; #pragma unroll
;         for (int mt = 0; mt < 2; ++mt)
; #pragma unroll
;             for (int s = 0; s < 2; ++s) vf[mt][s] = *(const LAS bf16x8*)(c.wl + 4096 + c.vfo[mt][s]);
;         const unsigned W = Wn >> h8;
;         const int dlo = t0 - kt * 32 - 31;
;         float ub = 0.f; bool uni = false;
;         if (dlo >= 182) { const unsigned ua = __builtin_amdgcn_readfirstlane(__float_as_uint(c.lut[dlo])), ue = __builtin_amdgcn_readfirstlane(__float_as_uint(c.lut[dlo + 62])); uni = (ua == ue); ub = __uint_as_float(ua); }
;         asm volatile("s_waitcnt lgkmcnt(0)" ::: "memory");
;         if (kt < hi) { attn_dma(c, kt + 1); if (MODE == 0) Wn = maskrow[kt + 1]; }
.LBB0_347:
	s_waitcnt vmcnt(0)
	ds_read_b128 v[50:53], v214
	ds_read_b128 v[90:93], v215
	ds_read_b128 v[94:97], v216
	ds_read_b128 v[86:89], v217
	ds_read_b128 v[82:85], v218 offset:4096
	ds_read_b128 v[6:9], v218 offset:6144
	ds_read_b128 v[10:13], v219 offset:4096
	ds_read_b128 v[2:5], v219 offset:6144
	s_waitcnt lgkmcnt(0)
	s_cmp_ge_u32 s60, s61
	s_cbranch_scc1 .LBB0_349
	s_ashr_i32 s7, s6, 31
	s_mul_i32 s66, s6, 0x1600
	s_mul_hi_i32 s67, s6, 0x1600
	s_add_u32 s66, s46, s66
	s_addc_u32 s67, s47, s67
	s_mov_b32 m0, s49
	s_nop 0
	global_load_lds_dwordx4 v116, s[66:67] sc0
	s_mov_b32 m0, s62
	s_nop 0
	global_load_lds_dwordx4 v118, s[66:67] sc0
	s_mov_b32 m0, s63
	s_nop 0
	global_load_lds_dwordx4 v122, s[66:67] sc0
	s_mov_b32 m0, s53
	s_nop 0
	global_load_lds_dwordx4 v126, s[66:67] sc0
	s_lshl_b64 s[66:67], s[6:7], 1
	s_add_u32 s68, s4, s66
	s_addc_u32 s69, s5, s67
	s_mov_b32 m0, s2
	s_nop 0
	global_load_lds_dwordx4 v114, s[68:69] sc0
	s_mov_b32 m0, s54
	s_nop 0
	global_load_lds_dwordx4 v120, s[68:69] sc0
	s_mov_b32 m0, s64
	s_nop 0
	global_load_lds_dwordx4 v124, s[68:69] sc0
	s_mov_b32 m0, s55
	s_nop 0
	global_load_lds_dwordx4 v128, s[68:69] sc0

; #define LAS __attribute__((address_space(3)))
; DI void attn_dma(const AttnCtx& c, int kt) {
;     const char* kb = (const char*)(c.kg + (size_t)(kt * 32 * c.krs) * RM_LD);
;     const char* vb = (const char*)(c.vg + kt * 32);
; #pragma unroll
;     for (int j = 0; j < 4; ++j) __builtin_amdgcn_global_load_lds((const unsigned*)(kb + c.koff[j]), (LAS unsigned*)(c.wl + j * 1024), 16, 0, 0);
; #pragma unroll
;     for (int j = 0; j < 4; ++j) __builtin_amdgcn_global_load_lds((const unsigned*)(vb + c.voff[j]), (LAS unsigned*)(c.wl + 4096 + j * 1024), 16, 0, 0);
; }
; template <int MODE>
; DI void attn_range(const AttnCtx& c, const bf16x8 (&qf)[4], int lo, int hi, int t0, int d00, AttnSt& st, const unsigned* maskrow, int h8, int win, int dmask, bool lane_sel) {
;     ...
;     for (int kt = lo; kt <= hi; ++kt) {
;         asm volatile("s_waitcnt vmcnt(0)" ::: "memory");
;         bf16x8 kf[4], vf[2][2];
; #pragma unroll
;         for (int ks = 0; ks < 4; ++ks) kf[ks] = *(const LAS bf16x8*)(c.wl + c.kfo[ks]);
; #pragma unroll
;         for (int mt = 0; mt < 2; ++mt)
; #pragma unroll
;             for (int s = 0; s < 2; ++s) vf[mt][s] = *(const LAS bf16x8*)(c.wl + 4096 + c.vfo[mt][s]);
;         const unsigned W = Wn >> h8;
;         const int dlo = t0 - kt * 32 - 31;
;         float ub = 0.f; bool uni = false;
;         if (dlo >= 182) { const unsigned ua = __builtin_amdgcn_readfirstlane(__float_as_uint(c.lut[dlo])), ue = __builtin_amdgcn_readfirstlane(__float_as_uint(c.lut[dlo + 62])); uni = (ua == ue); ub = __uint_as_float(ua); }
;         asm volatile("s_waitcnt lgkmcnt(0)" ::: "memory");
;         if (kt < hi) { attn_dma(c, kt + 1); if (MODE == 0) Wn = maskrow[kt + 1]; }
.LBB0_359:
	s_waitcnt vmcnt(0)
	ds_read_b128 v[50:53], v214
	ds_read_b128 v[90:93], v215
	ds_read_b128 v[94:97], v216
	ds_read_b128 v[86:89], v217
	ds_read_b128 v[82:85], v218 offset:4096
	ds_read_b128 v[6:9], v218 offset:6144
	ds_read_b128 v[10:13], v219 offset:4096
	ds_read_b128 v[2:5], v219 offset:6144
	s_waitcnt lgkmcnt(0)
	s_cmp_ge_i32 s2, s57
	s_cselect_b64 s[6:7], -1, 0
	s_and_b64 vcc, exec, s[6:7]
	s_cbranch_vccnz .LBB0_361
	s_ashr_i32 s1, s0, 31
	s_mul_i32 s61, s0, 0x1600
	s_mul_hi_i32 s8, s0, 0x1600
	s_add_u32 s62, s46, s61
	s_addc_u32 s63, s47, s8
	s_mov_b32 m0, s49
	s_nop 0
	global_load_lds_dwordx4 v116, s[62:63] sc0
	s_mov_b32 m0, s9
	s_nop 0
	global_load_lds_dwordx4 v118, s[62:63] sc0
	s_mov_b32 m0, s58
	s_nop 0
	global_load_lds_dwordx4 v122, s[62:63] sc0
	s_mov_b32 m0, s53
	s_nop 0
	global_load_lds_dwordx4 v126, s[62:63] sc0
	s_lshl_b64 s[62:63], s[0:1], 1
	s_add_u32 s64, s4, s62
	s_addc_u32 s65, s5, s63
	s_mov_b32 m0, s59
	s_nop 0
	global_load_lds_dwordx4 v114, s[64:65] sc0
	s_mov_b32 m0, s54
	s_nop 0
	global_load_lds_dwordx4 v120, s[64:65] sc0
	s_mov_b32 m0, s60
	s_nop 0
	global_load_lds_dwordx4 v124, s[64:65] sc0
	s_mov_b32 m0, s55
	s_nop 0
	global_load_lds_dwordx4 v128, s[64:65] sc0

; DI void load_lut(float* lut, const float* glut, int col, int lane) {
;     __builtin_amdgcn_fence(__ATOMIC_ACQ_REL, "wavefront");
;     f32x4 t[8];
; #pragma unroll
;     for (int k = 0; k < 8; ++k) t[k] = *(const f32x4*)(glut + (size_t)col * 2048 + k * 256 + lane * 4);
; #pragma unroll
;     for (int k = 0; k < 8; ++k) *(f32x4*)(lut + k * 256 + lane * 4) = t[k];
;     __builtin_amdgcn_fence(__ATOMIC_ACQ_REL, "wavefront");
;     __builtin_amdgcn_wave_barrier();
; }
; DI void g2_job(const Args& a, unsigned char* wsh, LAS unsigned char* wl, int b, int slot, int cls, int it, const int tid) {
;     ...
;     load_lut(lut, glut, 6 + 2 * 4 + slot, lane);
;     const int tq = tok0 + cls + 16 * (32 * it + r);
;     bf16x8 qf[4];
;     const bf16_t* qp = prm + (size_t)tq * RM_LD + C_BQ + (2 * 4 + slot) * 64 + 8 * h;
; #pragma unroll
;     for (int ks = 0; ks < 4; ++ks) qf[ks] = *(const bf16x8*)(qp + 16 * ks);
;     c.kg = prm + (size_t)(tok0 + cls) * RM_LD + C_BK + slot * 64;
;     c.vg = vt16 + (size_t)(slot * 64) * MTOK + tok0 + cls * 128;
;     attn_range<4>(c, qf, 0, it, 0, d00, st, nullptr, 0, 0, 0, false);
.LBB0_521:
	s_lshl_b32 s0, s40, 17
	s_and_b32 s2, s0, 0x1800000
	s_and_b32 s0, s41, 0xfffff800
	s_bfe_u32 s43, s40, 0x40002
	s_ashr_i32 s1, s0, 31
	s_lshl_b32 s44, s43, 8
	s_lshl_b64 s[4:5], s[0:1], 1
	s_or_b32 s1, s4, s44
	s_add_u32 s4, s1, s2
	s_addc_u32 s5, s5, 0
	s_or_b32 s0, s0, s43
	s_lshl_b32 s2, s40, 1
	s_mul_hi_i32 s1, s0, 0x1600
	s_mulk_i32 s0, 0x1600
	s_and_b32 s2, s2, 0x180
	s_or_b32 s0, s0, s2
	v_lshl_add_u64 v[138:139], s[0:1], 0, v[120:121]
	v_lshl_add_u64 v[140:141], s[0:1], 0, v[122:123]
	v_lshl_add_u64 v[142:143], s[0:1], 0, v[124:125]
	v_lshl_add_u64 v[144:145], s[0:1], 0, v[126:127]
	s_lshl_b32 s0, s42, 3
	s_add_i32 s0, s0, s6
	s_bfe_u32 s43, s0, 0x20006
	s_bfe_u32 s45, s0, 0x40002
	s_lshl_b32 s0, s0, 3
	s_and_b32 s0, s0, 0xfffff800
	s_lshl_b32 s1, s43, 13
	v_lshl_add_u64 v[130:131], s[4:5], 0, v[100:101]
	v_lshl_add_u64 v[132:133], s[4:5], 0, v[114:115]
	v_lshl_add_u64 v[134:135], s[4:5], 0, v[116:117]
	v_lshl_add_u64 v[136:137], s[4:5], 0, v[118:119]
	s_add_u32 s4, s92, s1
	s_addc_u32 s5, s93, 0
	v_lshl_add_u64 v[2:3], s[4:5], 0, v[0:1]
	s_mov_b32 s1, 0x471d000
	s_mov_b64 s[4:5], 0x471c000
	v_add_co_u32_e32 v30, vcc, s1, v2
	v_lshl_add_u64 v[14:15], v[2:3], 0, s[4:5]
	s_nop 0
	v_addc_co_u32_e32 v31, vcc, 0, v3, vcc
	global_load_dwordx4 v[2:5], v[30:31], off offset:-4096
	global_load_dwordx4 v[6:9], v[14:15], off offset:1024
	global_load_dwordx4 v[10:13], v[14:15], off offset:2048
	s_nop 0
	global_load_dwordx4 v[14:17], v[14:15], off offset:3072
	s_nop 0
	global_load_dwordx4 v[18:21], v[30:31], off
	global_load_dwordx4 v[22:25], v[30:31], off offset:1024
	global_load_dwordx4 v[26:29], v[30:31], off offset:2048
	s_nop 0
	global_load_dwordx4 v[30:33], v[30:31], off offset:3072
	v_readlane_b32 s46, v254, 55
	s_or_b32 s1, s45, s0
	v_readlane_b32 s47, v254, 56
	v_or_b32_e32 v146, s1, v150
	s_movk_i32 s2, 0x1600
	v_mov_b32_e32 v99, v1
	s_mov_b32 m0, s7
	s_mov_b32 s44, 0
	v_ashrrev_i32_e32 v147, 31, v146
	v_mov_b32_e32 v160, 0xf149f2ca
	s_add_i32 s98, s7, 0x1fa4
	v_lshl_add_u32 v129, v151, 2, s98
	v_mov_b32_e32 v159, v151
	s_waitcnt vmcnt(0)
	v_subrev_u32_e32 v161, s7, v149
	s_add_i32 s98, s7, 0x2000
	v_lshrrev_b32_e32 v161, 4, v161
	v_add_u32_e32 v161, s98, v161
	s_mov_b64 s[98:99], exec
	s_mov_b32 exec_lo, 0x11111111
	s_mov_b32 exec_hi, 0x11111111
	ds_write_b32 v161, v2
	ds_write_b32 v161, v6 offset:64
	ds_write_b32 v161, v10 offset:128
	ds_write_b32 v161, v14 offset:192
	ds_write_b32 v161, v18 offset:256
	ds_write_b32 v161, v22 offset:320
	ds_write_b32 v161, v26 offset:384
	ds_write_b32 v161, v30 offset:448
	s_mov_b64 exec, s[98:99]
	v_mov_b64_e32 v[2:3], s[46:47]
	v_mad_i64_i32 v[2:3], s[4:5], v146, s2, v[2:3]
	s_lshl_b32 s2, s43, 7
	s_mul_hi_i32 s4, s1, 0x1600
	s_mulk_i32 s1, 0x1600
	s_add_u32 s1, s46, s1
	s_addc_u32 s5, s47, s4
	s_add_u32 s4, s1, s2
	s_addc_u32 s5, s5, 0
	s_lshl_b32 s1, s43, 23
	v_readlane_b32 s46, v251, 32
	v_lshl_add_u64 v[2:3], v[2:3], 0, s[2:3]
	v_readlane_b32 s47, v251, 33
	s_add_u32 s2, s46, s1
	s_addc_u32 s46, s47, 0
	s_ashr_i32 s1, s0, 31
	s_lshl_b64 s[0:1], s[0:1], 1
	v_lshl_add_u64 v[2:3], v[2:3], 0, v[98:99]
	s_add_u32 s0, s2, s0
	global_load_dwordx4 v[50:53], v[2:3], off offset:3072
	global_load_dwordx4 v[54:57], v[2:3], off offset:3104
	global_load_dwordx4 v[58:61], v[2:3], off offset:3136
	global_load_dwordx4 v[62:65], v[2:3], off offset:3168
	s_addc_u32 s1, s46, s1
	s_lshl_b32 s2, s45, 8
	v_lshl_add_u64 v[2:3], s[4:5], 0, v[96:97]
	s_add_u32 s0, s0, s2
	v_lshl_add_u64 v[2:3], v[2:3], 0, s[20:21]
	s_addc_u32 s1, s1, 0
	global_load_lds_dwordx4 v[2:3], off
	v_lshl_add_u64 v[2:3], s[4:5], 0, v[102:103]
	s_add_i32 s2, s7, 0x400
	v_lshl_add_u64 v[2:3], v[2:3], 0, s[20:21]
	s_mov_b32 m0, s2
	s_add_i32 s45, s7, 0x800
	global_load_lds_dwordx4 v[2:3], off
	v_lshl_add_u64 v[2:3], s[4:5], 0, v[106:107]
	v_lshl_add_u64 v[2:3], v[2:3], 0, s[20:21]
	s_mov_b32 m0, s45
	s_add_i32 s46, s7, 0x1400
	global_load_lds_dwordx4 v[2:3], off
	v_lshl_add_u64 v[2:3], s[4:5], 0, v[110:111]
	s_add_i32 s4, s7, 0xc00
	v_lshl_add_u64 v[2:3], v[2:3], 0, s[20:21]
	s_mov_b32 m0, s4
	s_add_i32 s5, s7, 0x1000
	global_load_lds_dwordx4 v[2:3], off
	v_lshl_add_u64 v[2:3], s[0:1], 0, v[94:95]
	s_mov_b32 m0, s5
	s_add_i32 s47, s7, 0x1800
	global_load_lds_dwordx4 v[2:3], off
	v_lshl_add_u64 v[2:3], s[0:1], 0, v[104:105]
	s_mov_b32 m0, s46
	v_mov_b32_e32 v16, v1
	global_load_lds_dwordx4 v[2:3], off
	v_lshl_add_u64 v[2:3], s[0:1], 0, v[108:109]
	s_mov_b32 m0, s47
	v_mov_b32_e32 v17, v1
	global_load_lds_dwordx4 v[2:3], off
	v_lshl_add_u64 v[2:3], s[0:1], 0, v[112:113]
	s_add_i32 s0, s7, 0x1c00
	s_mov_b32 m0, s0
	v_mov_b32_e32 v4, v1
	global_load_lds_dwordx4 v[2:3], off
	v_mov_b32_e32 v2, v1
	v_mov_b32_e32 v3, v1
	v_mov_b32_e32 v5, v1
	v_mov_b32_e32 v6, v1
	v_mov_b32_e32 v7, v1
	v_mov_b32_e32 v8, v1
	v_mov_b32_e32 v9, v1
	v_mov_b32_e32 v10, v1
	v_mov_b32_e32 v11, v1
	v_mov_b32_e32 v12, v1
	v_mov_b32_e32 v13, v1
	v_mov_b32_e32 v14, v1
	v_mov_b32_e32 v15, v1
	v_mov_b64_e32 v[32:33], v[16:17]
	v_mov_b32_e32 v99, 0
	v_mov_b64_e32 v[30:31], v[14:15]
	v_mov_b64_e32 v[28:29], v[12:13]
	v_mov_b64_e32 v[26:27], v[10:11]
	v_mov_b64_e32 v[24:25], v[8:9]
	v_mov_b64_e32 v[22:23], v[6:7]
	v_mov_b64_e32 v[20:21], v[4:5]
	v_mov_b64_e32 v[18:19], v[2:3]
	s_waitcnt vmcnt(0)

; #define LAS __attribute__((address_space(3)))
; #define MFMA32(a, b, c) __builtin_amdgcn_mfma_f32_32x32x16_bf16((a), (b), (c), 0, 0, 0)
; template <int MODE, bool UNI>
; DI void attn_compute(const bf16x8 (&qf)[4], const bf16x8 (&kf)[4], const bf16x8 (&vf)[2][2], int kt, int d00, const float* lut, float ubias, AttnSt& st,
;                      unsigned W, int win, int dmask, bool lane_sel) {
;     const int s0 = kt * 32;
;     const int d0 = d00 - s0;
;     const LAS float* lb = (const LAS float*)lut + ((MODE == 4) ? 16 * (d0 - 23) : (d0 - 23));
;     float bia[16];
;     if (!UNI) {
; #pragma unroll
;         for (int i = 0; i < 16; ++i) { const int ci = 16 * (i >> 3) + (i & 7); bia[i] = (MODE == 4) ? lb[16 * (23 - ci)] : lb[23 - ci]; }
;     }
;     f32x16 sx;
; #pragma unroll
;     for (int i = 0; i < 16; ++i) sx[i] = 0.f;
; #pragma unroll
;     for (int ks = 0; ks < 4; ++ks) sx = MFMA32(kf[ks], qf[ks], sx);
;     asm volatile("s_waitcnt lgkmcnt(0)" ::: "memory");
;     float sv[16]; float mx = NEGF;
; #pragma unroll
;     for (int i = 0; i < 16; ++i) {
;         const int ci = 16 * (i >> 3) + (i & 7);
;         const int dist = d0 - ci;
;         bool v;
;         if (MODE == 0) v = ((W >> ci) & 1u) != 0u;
;         else if (MODE == 1) v = ((unsigned)dist <= (unsigned)win) && ((dist & dmask) == 0);
;         else if (MODE == 2) v = lane_sel;
;         else v = dist >= 0;
;         const float bias = UNI ? ubias : bia[i];
;         float s = fmaf(sx[i], SC2, bias);
;         if (MODE == 0) { const unsigned t = (unsigned)__builtin_amdgcn_sbfe((int)W, ci, 1);
;             s = __uint_as_float((__float_as_uint(s) & t) | (__float_as_uint(NEGF) & ~t)); }
;         else s = v ? s : NEGF;
;         sv[i] = s; mx = fmaxf(mx, s);
;     }
;     mx = fmaxf(mx, __shfl_xor(mx, 32));
;     const float mnew = fmaxf(st.m, mx);
;     const float msafe = (mnew > -1e29f) ? mnew : 0.f;
;     if (__ballot(mnew > st.m) != 0ull) {
;         const float alpha = __builtin_amdgcn_exp2f(st.m - msafe);
;         st.l *= alpha; st.m = mnew;
; #pragma unroll
;         for (int i = 0; i < 16; ++i) { st.o0[i] *= alpha; st.o1[i] *= alpha; }
;     }
.LBB0_524:
	s_waitcnt lgkmcnt(0)
	v_mfma_f32_32x32x16_bf16 v[34:49], v[34:37], v[50:53], 0
	s_nop 0
	v_cmp_lt_i32_e32 vcc, -1, v159
	v_mfma_f32_32x32x16_bf16 v[34:49], v[90:93], v[54:57], v[34:49]
	ds_read2_b32 v[90:91], v129 offset0:22 offset1:23
	v_mfma_f32_32x32x16_bf16 v[34:49], v[86:89], v[58:61], v[34:49]
	ds_read2_b32 v[86:87], v129 offset0:20 offset1:21
	ds_read2_b32 v[88:89], v129 offset0:18 offset1:19
	ds_read2_b32 v[92:93], v129 offset0:6 offset1:7
	ds_read2_b32 v[162:163], v129 offset0:4 offset1:5
	ds_read2_b32 v[164:165], v129 offset0:2 offset1:3
	ds_read2_b32 v[166:167], v129 offset1:1
	ds_read2_b32 v[168:169], v129 offset0:16 offset1:17
	s_waitcnt lgkmcnt(0)
	v_mfma_f32_32x32x16_bf16 v[34:49], v[82:85], v[62:65], v[34:49]
	s_waitcnt lgkmcnt(0)
	s_nop 10
	v_fmamk_f32 v34, v34, 0x3e38aa3b, v91
	v_fmac_f32_e32 v90, 0x3e38aa3b, v35
	v_cndmask_b32_e32 v35, v239, v34, vcc
	v_cmp_lt_i32_e32 vcc, 0, v159
	v_fmamk_f32 v36, v36, 0x3e38aa3b, v87
	v_fmac_f32_e32 v88, 0x3e38aa3b, v39
	v_cndmask_b32_e32 v39, v239, v90, vcc
	v_cmp_lt_i32_e32 vcc, 1, v159
	v_fmac_f32_e32 v86, 0x3e38aa3b, v37
	v_fmamk_f32 v82, v40, 0x3e38aa3b, v169
	v_cndmask_b32_e32 v40, v239, v36, vcc
	v_cmp_lt_i32_e32 vcc, 2, v159
	v_fmamk_f32 v37, v38, 0x3e38aa3b, v89
	v_fmac_f32_e32 v168, 0x3e38aa3b, v41
	v_cndmask_b32_e32 v36, v239, v86, vcc
	v_cmp_lt_i32_e32 vcc, 3, v159
	v_fmamk_f32 v41, v42, 0x3e38aa3b, v93
	v_fmac_f32_e32 v92, 0x3e38aa3b, v43
	v_cndmask_b32_e32 v37, v239, v37, vcc
	v_cmp_lt_i32_e32 vcc, 4, v159
	v_max3_f32 v34, v35, s30, v39
	v_max3_f32 v34, v34, v40, v36
	v_cndmask_b32_e32 v38, v239, v88, vcc
	v_cmp_lt_i32_e32 vcc, 5, v159
	v_fmac_f32_e32 v162, 0x3e38aa3b, v45
	v_max3_f32 v34, v34, v37, v38
	v_cndmask_b32_e32 v82, v239, v82, vcc
	v_cmp_lt_i32_e32 vcc, 6, v159
	v_fmac_f32_e32 v164, 0x3e38aa3b, v47
	v_fmac_f32_e32 v166, 0x3e38aa3b, v49
	v_cndmask_b32_e32 v83, v239, v168, vcc
	v_cmp_lt_i32_e32 vcc, 15, v159
	v_max3_f32 v34, v34, v82, v83
	s_nop 0
	v_cndmask_b32_e32 v84, v239, v41, vcc
	v_cmp_lt_i32_e32 vcc, 16, v159
	v_fmamk_f32 v41, v44, 0x3e38aa3b, v163
	s_nop 0
	v_cndmask_b32_e32 v43, v239, v92, vcc
	v_cmp_lt_i32_e32 vcc, 17, v159
	v_max3_f32 v34, v34, v84, v43
	s_nop 0
	v_cndmask_b32_e32 v44, v239, v41, vcc
	v_cmp_lt_i32_e32 vcc, 18, v159
	v_fmamk_f32 v41, v46, 0x3e38aa3b, v165
	s_nop 0
	v_cndmask_b32_e32 v45, v239, v162, vcc
	v_cmp_lt_i32_e32 vcc, 19, v159
	v_max3_f32 v34, v34, v44, v45
	s_nop 0
	v_cndmask_b32_e32 v46, v239, v41, vcc
	v_cmp_lt_i32_e32 vcc, 20, v159
	v_fmamk_f32 v41, v48, 0x3e38aa3b, v167
	s_nop 0
	v_cndmask_b32_e32 v47, v239, v164, vcc
	v_cmp_lt_i32_e32 vcc, 21, v159
	v_max3_f32 v34, v34, v46, v47
	s_nop 0
	v_cndmask_b32_e32 v48, v239, v41, vcc
	v_cmp_lt_i32_e32 vcc, 22, v159
	s_nop 1
	v_cndmask_b32_e32 v41, v239, v166, vcc
	v_max3_f32 v34, v34, v48, v41
	ds_bpermute_b32 v42, v148, v34
	s_waitcnt lgkmcnt(0)
	v_max3_f32 v34, v160, v34, v42
	v_cmp_lt_f32_e32 vcc, s12, v34
	s_nop 1
	v_cndmask_b32_e32 v42, 0, v34, vcc
	v_cmp_gt_f32_e32 vcc, v34, v160
	s_cbranch_vccz .LBB0_526
	v_sub_f32_e32 v49, v160, v42
	v_exp_f32_e32 v86, v49
	s_nop 0
	v_mul_f32_e32 v99, v99, v86
	v_pk_mul_f32 v[16:17], v[16:17], v[86:87] op_sel_hi:[1,0]
	v_pk_mul_f32 v[14:15], v[14:15], v[86:87] op_sel_hi:[1,0]
	v_pk_mul_f32 v[12:13], v[12:13], v[86:87] op_sel_hi:[1,0]
	v_pk_mul_f32 v[10:11], v[10:11], v[86:87] op_sel_hi:[1,0]
	v_pk_mul_f32 v[8:9], v[8:9], v[86:87] op_sel_hi:[1,0]
	v_pk_mul_f32 v[6:7], v[6:7], v[86:87] op_sel_hi:[1,0]
	v_pk_mul_f32 v[4:5], v[4:5], v[86:87] op_sel_hi:[1,0]
	v_pk_mul_f32 v[2:3], v[2:3], v[86:87] op_sel_hi:[1,0]
	v_pk_mul_f32 v[32:33], v[32:33], v[86:87] op_sel_hi:[1,0]
	v_pk_mul_f32 v[30:31], v[30:31], v[86:87] op_sel_hi:[1,0]
	v_pk_mul_f32 v[28:29], v[28:29], v[86:87] op_sel_hi:[1,0]
	v_pk_mul_f32 v[26:27], v[26:27], v[86:87] op_sel_hi:[1,0]
	v_pk_mul_f32 v[24:25], v[24:25], v[86:87] op_sel_hi:[1,0]
	v_pk_mul_f32 v[22:23], v[22:23], v[86:87] op_sel_hi:[1,0]
	v_pk_mul_f32 v[20:21], v[20:21], v[86:87] op_sel_hi:[1,0]
	v_pk_mul_f32 v[18:19], v[18:19], v[86:87] op_sel_hi:[1,0]
	s_branch .LBB0_527

; #define LAS __attribute__((address_space(3)))
; template <int MODE, bool UNI>
; DI void attn_compute(const bf16x8 (&qf)[4], const bf16x8 (&kf)[4], const bf16x8 (&vf)[2][2], int kt, int d00, const float* lut, float ubias, AttnSt& st,
;                      unsigned W, int win, int dmask, bool lane_sel) {
;     ...
;     float ps = 0.f; float p[16];
; #pragma unroll
;     for (int i = 0; i < 16; ++i) { const float e = __builtin_amdgcn_exp2f(sv[i] - msafe); p[i] = e; ps += e; }
;     st.l += ps;
;     u32x4 w0, w1;
;     w0.x = pk2(p[0], p[1]); w0.y = pk2(p[2], p[3]); w0.z = pk2(p[4], p[5]); w0.w = pk2(p[6], p[7]);
;     w1.x = pk2(p[8], p[9]); w1.y = pk2(p[10], p[11]); w1.z = pk2(p[12], p[13]); w1.w = pk2(p[14], p[15]);
;     const bf16x8 pf0 = __builtin_bit_cast(bf16x8, w0), pf1 = __builtin_bit_cast(bf16x8, w1);
;     st.o0 = MFMA32(vf[0][0], pf0, st.o0); st.o0 = MFMA32(vf[0][1], pf1, st.o0);
;     st.o1 = MFMA32(vf[1][0], pf0, st.o1); st.o1 = MFMA32(vf[1][1], pf1, st.o1);
; template <int MODE>
; DI void attn_range(const AttnCtx& c, const bf16x8 (&qf)[4], int lo, int hi, int t0, int d00, AttnSt& st, const unsigned* maskrow, int h8, int win, int dmask, bool lane_sel) {
;     ...
;     for (int kt = lo; kt <= hi; ++kt) {
;         asm volatile("s_waitcnt vmcnt(0)" ::: "memory");
;         bf16x8 kf[4], vf[2][2];
; #pragma unroll
;         for (int ks = 0; ks < 4; ++ks) kf[ks] = *(const LAS bf16x8*)(c.wl + c.kfo[ks]);
; #pragma unroll
;         for (int mt = 0; mt < 2; ++mt)
; #pragma unroll
;             for (int s = 0; s < 2; ++s) vf[mt][s] = *(const LAS bf16x8*)(c.wl + 4096 + c.vfo[mt][s]);
;         const unsigned W = Wn >> h8;
;         const int dlo = t0 - kt * 32 - 31;
;         float ub = 0.f; bool uni = false;
;         if (dlo >= 182) { const unsigned ua = __builtin_amdgcn_readfirstlane(__float_as_uint(c.lut[dlo])), ue = __builtin_amdgcn_readfirstlane(__float_as_uint(c.lut[dlo + 62])); uni = (ua == ue); ub = __uint_as_float(ua); }
;         asm volatile("s_waitcnt lgkmcnt(0)" ::: "memory");
;         if (kt < hi) { attn_dma(c, kt + 1); if (MODE == 0) Wn = maskrow[kt + 1]; }
;         if (MODE == 1 && dmask != 0) attn_compute_sp4(qf, kf, vf, kt, d00, c.lut, st, win, dmask);
;         else attn_compute<MODE, false>(qf, kf, vf, kt, d00, c.lut, 0.f, st, W, win, dmask, lane_sel);
;     }
.LBB0_527:
	v_sub_f32_e32 v36, v36, v42
	v_exp_f32_e32 v85, v36
	v_sub_f32_e32 v36, v37, v42
	v_exp_f32_e32 v86, v36
	v_sub_f32_e32 v36, v38, v42
	v_exp_f32_e32 v87, v36
	v_sub_f32_e32 v36, v82, v42
	v_exp_f32_e32 v82, v36
	v_sub_f32_e32 v36, v83, v42
	v_sub_f32_e32 v35, v35, v42
	v_exp_f32_e32 v83, v36
	v_sub_f32_e32 v36, v84, v42
	v_exp_f32_e32 v35, v35
	v_sub_f32_e32 v39, v39, v42
	v_sub_f32_e32 v40, v40, v42
	v_exp_f32_e32 v84, v36
	v_sub_f32_e32 v36, v43, v42
	v_exp_f32_e32 v39, v39
	v_exp_f32_e32 v40, v40
	v_exp_f32_e32 v88, v36
	v_sub_f32_e32 v36, v44, v42
	v_exp_f32_e32 v44, v36
	v_sub_f32_e32 v36, v45, v42
	v_exp_f32_e32 v45, v36
	v_sub_f32_e32 v36, v46, v42
	v_add_f32_e32 v49, 0, v35
	v_exp_f32_e32 v46, v36
	v_sub_f32_e32 v36, v47, v42
	v_add_f32_e32 v49, v39, v49
	v_exp_f32_e32 v47, v36
	v_cvt_pk_bf16_f32 v36, v35, v39
	v_cvt_pk_bf16_f32 v37, v40, v85
	v_cvt_pk_bf16_f32 v38, v86, v87
	v_cvt_pk_bf16_f32 v39, v82, v83
	v_add_f32_e32 v49, v40, v49
	v_sub_f32_e32 v43, v48, v42
	v_mfma_f32_32x32x16_bf16 v[2:17], v[78:81], v[36:39], v[2:17]
	v_sub_f32_e32 v40, v41, v42
	v_add_f32_e32 v49, v85, v49
	v_exp_f32_e32 v35, v43
	v_exp_f32_e32 v48, v40
	v_add_f32_e32 v49, v86, v49
	v_add_f32_e32 v49, v87, v49
	v_add_f32_e32 v49, v82, v49
	v_mfma_f32_32x32x16_bf16 v[18:33], v[70:73], v[36:39], v[18:33]
	v_add_f32_e32 v49, v83, v49
	v_cvt_pk_bf16_f32 v40, v84, v88
	v_cvt_pk_bf16_f32 v41, v44, v45
	v_cvt_pk_bf16_f32 v42, v46, v47
	v_cvt_pk_bf16_f32 v43, v35, v48
	v_add_f32_e32 v49, v84, v49
	v_add_f32_e32 v49, v88, v49
	v_mfma_f32_32x32x16_bf16 v[2:17], v[74:77], v[40:43], v[2:17]
	v_add_f32_e32 v36, v44, v49
	v_add_f32_e32 v36, v45, v36
	v_add_f32_e32 v36, v46, v36
	v_add_f32_e32 v36, v47, v36
	v_add_f32_e32 v35, v35, v36
	v_add_f32_e32 v35, v48, v35
	s_add_i32 s44, s44, 1
	v_mfma_f32_32x32x16_bf16 v[18:33], v[66:69], v[40:43], v[18:33]
	v_add_f32_e32 v99, v35, v99
	v_lshl_add_u64 v[130:131], v[130:131], 0, 64
	v_lshl_add_u64 v[132:133], v[132:133], 0, 64
	v_lshl_add_u64 v[134:135], v[134:135], 0, 64
	v_lshl_add_u64 v[136:137], v[136:137], 0, 64
	v_lshl_add_u64 v[138:139], v[138:139], 0, s[96:97]
	v_lshl_add_u64 v[140:141], v[140:141], 0, s[96:97]
	v_lshl_add_u64 v[142:143], v[142:143], 0, s[96:97]
	v_lshl_add_u64 v[144:145], v[144:145], 0, s[96:97]
	v_subrev_u32_e32 v159, 32, v159
	s_cmp_lg_u32 s9, s44
	v_add_u32_e32 v129, 0xffffff80, v129
	s_cbranch_scc0 .LBB0_529
	v_mov_b32_e32 v160, v34
	s_branch .LBB0_522
